# lever 2 (prologue de-serialisation): inverse-RMS table fill of the RMSNorm-folded GEMM phases issues every trip's row-sum loads before the first wait
# speedup vs baseline: 1.0018x; 1.0018x over previous
.LBB0_164:
	s_mov_b32 s22, 0
	v_lshl_add_u64 v[2:3], v[2:3], 0, s[12:13]
	v_cmp_gt_i64_e32 vcc, s[18:19], v[2:3]
	s_cbranch_vccz .Lrs0_issued
	v_ashrrev_i32_e32 v78, 31, v10
	v_lshrrev_b32_e32 v78, 29, v78
	v_add_u32_e32 v78, v10, v78
	v_ashrrev_i32_e32 v80, 3, v78
	v_and_b32_e32 v78, -8, v78
	v_sub_u32_e32 v78, v10, v78
	v_cmp_gt_i32_e32 vcc, 0, v78
	v_add_u32_e32 v4, 2, v4
	s_nop 0
	v_cndmask_b32_e32 v81, v7, v8, vcc
	v_mad_u64_u32 v[80:81], s[4:5], v81, v78, v[80:81]
	v_mul_hi_i32 v78, v80, s21
	v_lshrrev_b32_e32 v81, 31, v78
	v_ashrrev_i32_e32 v78, 3, v78
	v_add_u32_e32 v78, v78, v81
	v_mul_lo_u32 v81, v78, 48
	v_sub_u32_e32 v80, v80, v81
	v_lshrrev_b16_sdwa v81, v9, sext(v80) dst_sel:DWORD dst_unused:UNUSED_PAD src0_sel:DWORD src1_sel:BYTE_0
	v_and_b32_e32 v81, 3, v81
	v_add_u16_e32 v81, v80, v81
	v_and_b32_e32 v81, 0xfc, v81
	v_sub_u16_e32 v80, v80, v81
	v_bfe_i32 v80, v80, 0, 8
	v_lshlrev_b32_e32 v78, 10, v78
	v_lshl_add_u32 v78, v80, 8, v78
	v_or_b32_sdwa v80, v78, v1 dst_sel:DWORD dst_unused:UNUSED_PAD src0_sel:DWORD src1_sel:BYTE_0
	v_ashrrev_i32_e32 v81, 31, v80
	v_lshlrev_b64 v[80:81], 6, v[80:81]
	v_lshl_add_u64 v[82:83], s[10:11], 0, v[80:81]
	global_load_dwordx4 v[12:15], v[82:83], off
	global_load_dwordx4 v[16:19], v[82:83], off offset:32
	global_load_dwordx4 v[20:23], v[82:83], off offset:16
	global_load_dwordx4 v[24:27], v[82:83], off offset:48
	v_add_u32_e32 v10, s24, v10
	s_add_i32 s22, s22, 1
	v_cmp_lt_i32_e32 vcc, 5, v4
	s_cbranch_vccnz .Lrs0_issued
	v_lshl_add_u64 v[2:3], v[2:3], 0, s[12:13]
	v_cmp_gt_i64_e32 vcc, s[18:19], v[2:3]
	s_cbranch_vccz .Lrs0_issued
	v_ashrrev_i32_e32 v78, 31, v10
	v_lshrrev_b32_e32 v78, 29, v78
	v_add_u32_e32 v78, v10, v78
	v_ashrrev_i32_e32 v80, 3, v78
	v_and_b32_e32 v78, -8, v78
	v_sub_u32_e32 v78, v10, v78
	v_cmp_gt_i32_e32 vcc, 0, v78
	v_add_u32_e32 v4, 2, v4
	s_nop 0
	v_cndmask_b32_e32 v81, v7, v8, vcc
	v_mad_u64_u32 v[80:81], s[4:5], v81, v78, v[80:81]
	v_mul_hi_i32 v78, v80, s21
	v_lshrrev_b32_e32 v81, 31, v78
	v_ashrrev_i32_e32 v78, 3, v78
	v_add_u32_e32 v78, v78, v81
	v_mul_lo_u32 v81, v78, 48
	v_sub_u32_e32 v80, v80, v81
	v_lshrrev_b16_sdwa v81, v9, sext(v80) dst_sel:DWORD dst_unused:UNUSED_PAD src0_sel:DWORD src1_sel:BYTE_0
	v_and_b32_e32 v81, 3, v81
	v_add_u16_e32 v81, v80, v81
	v_and_b32_e32 v81, 0xfc, v81
	v_sub_u16_e32 v80, v80, v81
	v_bfe_i32 v80, v80, 0, 8
	v_lshlrev_b32_e32 v78, 10, v78
	v_lshl_add_u32 v78, v80, 8, v78
	v_or_b32_sdwa v80, v78, v1 dst_sel:DWORD dst_unused:UNUSED_PAD src0_sel:DWORD src1_sel:BYTE_0
	v_ashrrev_i32_e32 v81, 31, v80
	v_lshlrev_b64 v[80:81], 6, v[80:81]
	v_lshl_add_u64 v[82:83], s[10:11], 0, v[80:81]
	global_load_dwordx4 v[30:33], v[82:83], off
	global_load_dwordx4 v[34:37], v[82:83], off offset:32
	global_load_dwordx4 v[38:41], v[82:83], off offset:16
	global_load_dwordx4 v[42:45], v[82:83], off offset:48
	v_add_u32_e32 v10, s24, v10
	s_add_i32 s22, s22, 1
	v_cmp_lt_i32_e32 vcc, 5, v4
	s_cbranch_vccnz .Lrs0_issued
	v_lshl_add_u64 v[2:3], v[2:3], 0, s[12:13]
	v_cmp_gt_i64_e32 vcc, s[18:19], v[2:3]
	s_cbranch_vccz .Lrs0_issued
	v_ashrrev_i32_e32 v78, 31, v10
	v_lshrrev_b32_e32 v78, 29, v78
	v_add_u32_e32 v78, v10, v78
	v_ashrrev_i32_e32 v80, 3, v78
	v_and_b32_e32 v78, -8, v78
	v_sub_u32_e32 v78, v10, v78
	v_cmp_gt_i32_e32 vcc, 0, v78
	v_add_u32_e32 v4, 2, v4
	s_nop 0
	v_cndmask_b32_e32 v81, v7, v8, vcc
	v_mad_u64_u32 v[80:81], s[4:5], v81, v78, v[80:81]
	v_mul_hi_i32 v78, v80, s21
	v_lshrrev_b32_e32 v81, 31, v78
	v_ashrrev_i32_e32 v78, 3, v78
	v_add_u32_e32 v78, v78, v81
	v_mul_lo_u32 v81, v78, 48
	v_sub_u32_e32 v80, v80, v81
	v_lshrrev_b16_sdwa v81, v9, sext(v80) dst_sel:DWORD dst_unused:UNUSED_PAD src0_sel:DWORD src1_sel:BYTE_0
	v_and_b32_e32 v81, 3, v81
	v_add_u16_e32 v81, v80, v81
	v_and_b32_e32 v81, 0xfc, v81
	v_sub_u16_e32 v80, v80, v81
	v_bfe_i32 v80, v80, 0, 8
	v_lshlrev_b32_e32 v78, 10, v78
	v_lshl_add_u32 v78, v80, 8, v78
	v_or_b32_sdwa v80, v78, v1 dst_sel:DWORD dst_unused:UNUSED_PAD src0_sel:DWORD src1_sel:BYTE_0
	v_ashrrev_i32_e32 v81, 31, v80
	v_lshlrev_b64 v[80:81], 6, v[80:81]
	v_lshl_add_u64 v[82:83], s[10:11], 0, v[80:81]
	global_load_dwordx4 v[46:49], v[82:83], off
	global_load_dwordx4 v[50:53], v[82:83], off offset:32
	global_load_dwordx4 v[54:57], v[82:83], off offset:16
	global_load_dwordx4 v[58:61], v[82:83], off offset:48
	v_add_u32_e32 v10, s24, v10
	s_add_i32 s22, s22, 1
	v_cmp_lt_i32_e32 vcc, 5, v4
	s_cbranch_vccnz .Lrs0_issued
	v_lshl_add_u64 v[2:3], v[2:3], 0, s[12:13]
	v_cmp_gt_i64_e32 vcc, s[18:19], v[2:3]
	s_cbranch_vccz .Lrs0_issued
	v_ashrrev_i32_e32 v78, 31, v10
	v_lshrrev_b32_e32 v78, 29, v78
	v_add_u32_e32 v78, v10, v78
	v_ashrrev_i32_e32 v80, 3, v78
	v_and_b32_e32 v78, -8, v78
	v_sub_u32_e32 v78, v10, v78
	v_cmp_gt_i32_e32 vcc, 0, v78
	v_add_u32_e32 v4, 2, v4
	s_nop 0
	v_cndmask_b32_e32 v81, v7, v8, vcc
	v_mad_u64_u32 v[80:81], s[4:5], v81, v78, v[80:81]
	v_mul_hi_i32 v78, v80, s21
	v_lshrrev_b32_e32 v81, 31, v78
	v_ashrrev_i32_e32 v78, 3, v78
	v_add_u32_e32 v78, v78, v81
	v_mul_lo_u32 v81, v78, 48
	v_sub_u32_e32 v80, v80, v81
	v_lshrrev_b16_sdwa v81, v9, sext(v80) dst_sel:DWORD dst_unused:UNUSED_PAD src0_sel:DWORD src1_sel:BYTE_0
	v_and_b32_e32 v81, 3, v81
	v_add_u16_e32 v81, v80, v81
	v_and_b32_e32 v81, 0xfc, v81
	v_sub_u16_e32 v80, v80, v81
	v_bfe_i32 v80, v80, 0, 8
	v_lshlrev_b32_e32 v78, 10, v78
	v_lshl_add_u32 v78, v80, 8, v78
	v_or_b32_sdwa v80, v78, v1 dst_sel:DWORD dst_unused:UNUSED_PAD src0_sel:DWORD src1_sel:BYTE_0
	v_ashrrev_i32_e32 v81, 31, v80
	v_lshlrev_b64 v[80:81], 6, v[80:81]
	v_lshl_add_u64 v[82:83], s[10:11], 0, v[80:81]
	global_load_dwordx4 v[62:65], v[82:83], off
	global_load_dwordx4 v[66:69], v[82:83], off offset:32
	global_load_dwordx4 v[70:73], v[82:83], off offset:16
	global_load_dwordx4 v[74:77], v[82:83], off offset:48
	v_add_u32_e32 v10, s24, v10
	s_add_i32 s22, s22, 1
.Lrs0_issued:
	s_cmp_le_u32 s22, 0
	s_cbranch_scc1 .Lrs0_done
	s_cmp_eq_u32 s22, 1
	s_cbranch_scc1 .Lrs0_w0_0
	s_waitcnt vmcnt(4)
	s_branch .Lrs0_r_0

.Lrs0_r_0:
	v_mov_b32_e32 v10, v12
	v_mov_b32_e32 v11, v16
	v_mov_b32_e32 v16, v13
	v_mov_b32_e32 v12, v14
	v_mov_b32_e32 v13, v18
	v_mov_b32_e32 v18, v15
	v_mov_b32_e32 v14, v20
	v_mov_b32_e32 v15, v24
	v_mov_b32_e32 v24, v21
	v_mov_b32_e32 v20, v22
	v_mov_b32_e32 v21, v26
	v_mov_b32_e32 v26, v23
	v_pk_add_f32 v[10:11], v[10:11], v[16:17]
	v_pk_add_f32 v[12:13], v[12:13], v[18:19]
	v_pk_add_f32 v[14:15], v[14:15], v[24:25]
	v_pk_add_f32 v[16:17], v[20:21], v[26:27]
	v_pk_add_f32 v[10:11], v[10:11], v[12:13]
	v_pk_add_f32 v[12:13], v[14:15], v[16:17]
	s_nop 0
	v_pk_add_f32 v[10:11], v[10:11], v[12:13]
	s_nop 0
	v_add_f32_e32 v10, v10, v11
	v_fmamk_f32 v10, v10, 0x3a800000, v6
	v_mul_f32_e32 v11, 0x4b800000, v10
	v_cmp_gt_f32_e32 vcc, s25, v10
	s_nop 1
	v_cndmask_b32_e32 v10, v10, v11, vcc
	v_rsq_f32_e32 v10, v10
	s_nop 0
	v_mul_f32_e32 v11, 0x45800000, v10
	v_cndmask_b32_e32 v10, v10, v11, vcc
	ds_write_b32 v5, v10
	v_add_u32_e32 v5, 0x800, v5
	s_cmp_le_u32 s22, 1
	s_cbranch_scc1 .Lrs0_done
	s_cmp_eq_u32 s22, 2
	s_cbranch_scc1 .Lrs0_w0_1
	s_waitcnt vmcnt(4)
	s_branch .Lrs0_r_1

.Lrs0_r_1:
	v_mov_b32_e32 v10, v30
	v_mov_b32_e32 v11, v34
	v_mov_b32_e32 v34, v31
	v_mov_b32_e32 v30, v32
	v_mov_b32_e32 v31, v36
	v_mov_b32_e32 v36, v33
	v_mov_b32_e32 v32, v38
	v_mov_b32_e32 v33, v42
	v_mov_b32_e32 v42, v39
	v_mov_b32_e32 v38, v40
	v_mov_b32_e32 v39, v44
	v_mov_b32_e32 v44, v41
	v_pk_add_f32 v[10:11], v[10:11], v[34:35]
	v_pk_add_f32 v[30:31], v[30:31], v[36:37]
	v_pk_add_f32 v[32:33], v[32:33], v[42:43]
	v_pk_add_f32 v[34:35], v[38:39], v[44:45]
	v_pk_add_f32 v[10:11], v[10:11], v[30:31]
	v_pk_add_f32 v[30:31], v[32:33], v[34:35]
	s_nop 0
	v_pk_add_f32 v[10:11], v[10:11], v[30:31]
	s_nop 0
	v_add_f32_e32 v10, v10, v11
	v_fmamk_f32 v10, v10, 0x3a800000, v6
	v_mul_f32_e32 v11, 0x4b800000, v10
	v_cmp_gt_f32_e32 vcc, s25, v10
	s_nop 1
	v_cndmask_b32_e32 v10, v10, v11, vcc
	v_rsq_f32_e32 v10, v10
	s_nop 0
	v_mul_f32_e32 v11, 0x45800000, v10
	v_cndmask_b32_e32 v10, v10, v11, vcc
	ds_write_b32 v5, v10
	v_add_u32_e32 v5, 0x800, v5
	s_cmp_le_u32 s22, 2
	s_cbranch_scc1 .Lrs0_done
	s_cmp_eq_u32 s22, 3
	s_cbranch_scc1 .Lrs0_w0_2
	s_waitcnt vmcnt(4)
	s_branch .Lrs0_r_2

.Lrs0_r_2:
	v_mov_b32_e32 v10, v46
	v_mov_b32_e32 v11, v50
	v_mov_b32_e32 v50, v47
	v_mov_b32_e32 v46, v48
	v_mov_b32_e32 v47, v52
	v_mov_b32_e32 v52, v49
	v_mov_b32_e32 v48, v54
	v_mov_b32_e32 v49, v58
	v_mov_b32_e32 v58, v55
	v_mov_b32_e32 v54, v56
	v_mov_b32_e32 v55, v60
	v_mov_b32_e32 v60, v57
	v_pk_add_f32 v[10:11], v[10:11], v[50:51]
	v_pk_add_f32 v[46:47], v[46:47], v[52:53]
	v_pk_add_f32 v[48:49], v[48:49], v[58:59]
	v_pk_add_f32 v[50:51], v[54:55], v[60:61]
	v_pk_add_f32 v[10:11], v[10:11], v[46:47]
	v_pk_add_f32 v[46:47], v[48:49], v[50:51]
	s_nop 0
	v_pk_add_f32 v[10:11], v[10:11], v[46:47]
	s_nop 0
	v_add_f32_e32 v10, v10, v11
	v_fmamk_f32 v10, v10, 0x3a800000, v6
	v_mul_f32_e32 v11, 0x4b800000, v10
	v_cmp_gt_f32_e32 vcc, s25, v10
	s_nop 1
	v_cndmask_b32_e32 v10, v10, v11, vcc
	v_rsq_f32_e32 v10, v10
	s_nop 0
	v_mul_f32_e32 v11, 0x45800000, v10
	v_cndmask_b32_e32 v10, v10, v11, vcc
	ds_write_b32 v5, v10
	v_add_u32_e32 v5, 0x800, v5
	s_cmp_le_u32 s22, 3
	s_cbranch_scc1 .Lrs0_done
	s_cmp_eq_u32 s22, 4
	s_cbranch_scc1 .Lrs0_w0_3
	s_waitcnt vmcnt(4)
	s_branch .Lrs0_r_3

.Lrs0_r_3:
	v_mov_b32_e32 v10, v62
	v_mov_b32_e32 v11, v66
	v_mov_b32_e32 v66, v63
	v_mov_b32_e32 v62, v64
	v_mov_b32_e32 v63, v68
	v_mov_b32_e32 v68, v65
	v_mov_b32_e32 v64, v70
	v_mov_b32_e32 v65, v74
	v_mov_b32_e32 v74, v71
	v_mov_b32_e32 v70, v72
	v_mov_b32_e32 v71, v76
	v_mov_b32_e32 v76, v73
	v_pk_add_f32 v[10:11], v[10:11], v[66:67]
	v_pk_add_f32 v[62:63], v[62:63], v[68:69]
	v_pk_add_f32 v[64:65], v[64:65], v[74:75]
	v_pk_add_f32 v[66:67], v[70:71], v[76:77]
	v_pk_add_f32 v[10:11], v[10:11], v[62:63]
	v_pk_add_f32 v[62:63], v[64:65], v[66:67]
	s_nop 0
	v_pk_add_f32 v[10:11], v[10:11], v[62:63]
	s_nop 0
	v_add_f32_e32 v10, v10, v11
	v_fmamk_f32 v10, v10, 0x3a800000, v6
	v_mul_f32_e32 v11, 0x4b800000, v10
	v_cmp_gt_f32_e32 vcc, s25, v10
	s_nop 1
	v_cndmask_b32_e32 v10, v10, v11, vcc
	v_rsq_f32_e32 v10, v10
	s_nop 0
	v_mul_f32_e32 v11, 0x45800000, v10
	v_cndmask_b32_e32 v10, v10, v11, vcc
	ds_write_b32 v5, v10
	v_add_u32_e32 v5, 0x800, v5
.Lrs0_done:
	s_branch .LBB0_166
.LBB0_166:
	s_or_b64 exec, exec, s[8:9]
	s_waitcnt lgkmcnt(0)
	s_barrier
	v_mov_b32_e32 v2, v0
	s_cmpk_gt_i32 s3, 0x2ff
	v_readfirstlane_b32 s6, v2
	s_cbranch_scc1 .LBB0_187
	v_bfe_i32 v4, v2, 27, 1
	v_lshlrev_b32_e32 v3, 4, v2
	v_lshrrev_b32_e32 v4, 22, v4
	v_add_u32_e32 v4, v3, v4
	v_and_b32_e32 v4, 0xfffffc00, v4
	v_sub_u32_e32 v4, v3, v4
	v_ashrrev_i32_e32 v1, 31, v2
	v_lshrrev_b32_e32 v5, 4, v4
	v_lshrrev_b32_e32 v1, 26, v1
	v_bitop3_b32 v4, v5, v4, 32 bitop3:0x6c
	v_add_u32_e32 v1, v2, v1
	v_ashrrev_i32_e32 v6, 31, v4
	v_ashrrev_i32_e32 v1, 6, v1
	v_lshrrev_b32_e32 v6, 26, v6
	v_lshlrev_b32_e32 v5, 3, v1
	v_add_u32_e32 v6, v4, v6
	v_and_b32_e32 v5, -16, v5
	v_ashrrev_i32_e32 v7, 6, v6
	v_and_b32_e32 v6, 0xc0, v6
	v_add_u32_e32 v5, v7, v5
	v_sub_u32_e32 v4, v4, v6
	v_mov_b32_e32 v6, 1
	v_lshlrev_b32_e32 v1, 5, v1
	v_ashrrev_i16_sdwa v4, v6, sext(v4) dst_sel:DWORD dst_unused:UNUSED_PAD src0_sel:DWORD src1_sel:BYTE_0
	v_lshlrev_b32_e32 v8, 1, v5
	v_lshrrev_b32_e32 v9, 2, v5
	v_and_b32_e32 v7, 3, v7
	s_mov_b32 s4, 0x1fffe0
	v_and_b32_e32 v1, 32, v1
	v_bfe_i32 v4, v4, 0, 16
	v_and_b32_e32 v8, 24, v8
	v_and_b32_e32 v9, 4, v9
	v_and_or_b32 v7, v5, s4, v7
	v_or3_b32 v7, v7, v9, v8
	v_add_lshl_u32 v4, v1, v4, 1
	v_add_u32_e32 v3, 0x2000, v3
	v_lshl_add_u32 v1, v5, 11, v4
	v_lshl_add_u32 v142, v7, 11, v4
	v_ashrrev_i32_e32 v4, 31, v3
	v_lshrrev_b32_e32 v4, 22, v4
	v_add_u32_e32 v4, v3, v4
	v_ashrrev_i32_e32 v4, 10, v4
	v_mul_i32_i24_e32 v5, 0x400, v4
	v_sub_u32_e32 v3, v3, v5
	v_lshrrev_b32_e32 v5, 4, v3
	v_bitop3_b32 v3, v5, v3, 32 bitop3:0x6c
	v_ashrrev_i32_e32 v7, 31, v3
	v_lshrrev_b32_e32 v7, 26, v7
	v_lshlrev_b32_e32 v5, 3, v4
	v_add_u32_e32 v7, v3, v7
	v_and_b32_e32 v5, -16, v5
	v_ashrrev_i32_e32 v8, 6, v7
	v_add_u32_e32 v5, v8, v5
	v_and_b32_e32 v8, 3, v8
	s_ashr_i32 s24, s6, 6
	s_ashr_i32 s7, s6, 8
	v_and_or_b32 v8, v5, s4, v8
	s_lshl_b32 s4, s24, 10
	s_waitcnt lgkmcnt(0)
	s_add_u32 s8, s16, 0x3a00000
	s_addc_u32 s5, s17, 0
	s_add_u32 s12, s16, 0x200000
	s_addc_u32 s9, s17, 0
	s_ashr_i32 s21, s3, 31
	s_lshr_b32 s10, s21, 29
	s_add_i32 s10, s3, s10
	s_ashr_i32 s11, s10, 3
	s_and_b32 s10, s10, -8
	s_sub_i32 s10, s3, s10
	s_cmp_lt_i32 s10, 0
	s_movk_i32 s26, 0x61
	s_cselect_b32 s13, s26, 0x60
	s_mul_i32 s10, s13, s10
	s_add_i32 s10, s10, s11
	s_mul_hi_i32 s11, s10, 0x2aaaaaab
	s_lshr_b32 s13, s11, 31
	s_ashr_i32 s11, s11, 3
	s_add_i32 s11, s11, s13
	s_lshl_b32 s13, s11, 2
	s_mul_i32 s11, s11, 48
	s_sub_i32 s10, s10, s11
	s_bfe_i32 s11, s10, 0x80000
	s_bfe_u32 s11, s11, 0x2000d
	v_and_b32_e32 v7, 0xc0, v7
	s_add_i32 s11, s10, s11
	v_sub_u32_e32 v3, v3, v7
	s_bfe_i32 s14, s11, 0x80000
	s_and_b32 s11, s11, 0xfc
	v_lshlrev_b32_e32 v4, 5, v4
	v_ashrrev_i16_sdwa v3, v6, sext(v3) dst_sel:DWORD dst_unused:UNUSED_PAD src0_sel:DWORD src1_sel:BYTE_0
	v_lshlrev_b32_e32 v6, 1, v5
	v_lshrrev_b32_e32 v7, 2, v5
	s_sext_i32_i16 s14, s14
	s_sub_i32 s10, s10, s11
	s_add_i32 s27, s4, 0
	v_and_b32_e32 v4, 32, v4
	v_bfe_i32 v3, v3, 0, 16
	v_and_b32_e32 v6, 24, v6
	v_and_b32_e32 v7, 4, v7
	s_sext_i32_i8 s10, s10
	s_ashr_i32 s56, s14, 2
	s_add_i32 s28, s27, 0x10000
	v_or3_b32 v6, v8, v7, v6
	v_add_lshl_u32 v3, v4, v3, 1
	s_add_i32 s57, s13, s10
	s_and_b32 s13, s9, 0xffff
	s_mov_b32 s15, 0x20000
	s_mov_b32 s14, 0x7ffffff0
	s_lshl_b32 s61, s56, 19
	s_mov_b32 m0, s28
	s_add_i32 s29, s27, 0x12000
	v_lshl_add_u32 v144, v6, 11, v3
	buffer_load_dwordx4 v142, s[12:15], s61 offen lds
	s_mov_b32 m0, s29
	s_add_i32 s30, s27, 0x14000
	buffer_load_dwordx4 v144, s[12:15], s61 offen lds
	s_or_b32 s4, s61, 0x40000
	s_mov_b32 m0, s30
	s_add_i32 s31, s27, 0x16000
	s_and_b32 s9, s5, 0xffff
	buffer_load_dwordx4 v142, s[12:15], s4 offen lds
	s_mov_b32 m0, s31
	s_mov_b32 s40, s8
	s_mov_b32 s41, s9
	s_mov_b32 s42, s14
	s_mov_b32 s43, s15
	buffer_load_dwordx4 v144, s[12:15], s4 offen lds
	s_lshl_b32 s62, s57, 19
	s_mov_b32 m0, s27
	s_add_i32 s34, s27, 0x2000
	v_lshl_add_u32 v143, v5, 11, v3
	buffer_load_dwordx4 v1, s[40:43], s62 offen lds
	s_mov_b32 m0, s34
	s_add_i32 s35, s27, 0x4000
	buffer_load_dwordx4 v143, s[40:43], s62 offen lds
	s_or_b32 s4, s62, 0x40000
	s_mov_b32 m0, s35
	s_add_i32 s36, s27, 0x6000
	buffer_load_dwordx4 v1, s[40:43], s4 offen lds
	s_mov_b32 m0, s36
	s_cmp_eq_u32 s7, 1
	buffer_load_dwordx4 v143, s[40:43], s4 offen lds
	s_mov_b32 s58, 0
	s_mov_b32 s10, s14
	s_cselect_b64 s[22:23], -1, 0
	s_cmp_lg_u32 s7, 1
	s_mov_b32 s11, s15
	s_cbranch_scc1 .LBB0_169
	s_barrier

.LBB0_509:
	s_mov_b32 s22, 0
	v_lshl_add_u64 v[2:3], v[2:3], 0, s[12:13]
	v_cmp_gt_i64_e32 vcc, s[18:19], v[2:3]
	s_cbranch_vccz .Lrs1_issued
	v_ashrrev_i32_e32 v78, 31, v10
	v_lshrrev_b32_e32 v78, 29, v78
	v_add_u32_e32 v78, v10, v78
	v_ashrrev_i32_e32 v80, 3, v78
	v_and_b32_e32 v78, -8, v78
	v_sub_u32_e32 v78, v10, v78
	v_cmp_gt_i32_e32 vcc, 0, v78
	v_add_u32_e32 v4, 2, v4
	s_nop 0
	v_cndmask_b32_e32 v81, v7, v8, vcc
	v_mad_u64_u32 v[80:81], s[4:5], v81, v78, v[80:81]
	v_mul_hi_i32 v78, v80, s17
	v_lshrrev_b32_e32 v81, 31, v78
	v_ashrrev_i32_e32 v78, 4, v78
	v_add_u32_e32 v78, v78, v81
	v_mul_lo_u32 v81, v78, s25
	v_sub_u32_e32 v80, v80, v81
	v_lshrrev_b16_sdwa v81, v9, sext(v80) dst_sel:DWORD dst_unused:UNUSED_PAD src0_sel:DWORD src1_sel:BYTE_0
	v_and_b32_e32 v81, 3, v81
	v_add_u16_e32 v81, v80, v81
	v_and_b32_e32 v81, 0xfc, v81
	v_sub_u16_e32 v80, v80, v81
	v_bfe_i32 v80, v80, 0, 8
	v_lshlrev_b32_e32 v78, 10, v78
	v_lshl_add_u32 v78, v80, 8, v78
	v_or_b32_sdwa v80, v78, v1 dst_sel:DWORD dst_unused:UNUSED_PAD src0_sel:DWORD src1_sel:BYTE_0
	v_ashrrev_i32_e32 v81, 31, v80
	v_lshlrev_b64 v[80:81], 6, v[80:81]
	v_lshl_add_u64 v[82:83], s[10:11], 0, v[80:81]
	global_load_dwordx4 v[12:15], v[82:83], off
	global_load_dwordx4 v[16:19], v[82:83], off offset:32
	global_load_dwordx4 v[20:23], v[82:83], off offset:16
	global_load_dwordx4 v[24:27], v[82:83], off offset:48
	v_add_u32_e32 v10, s24, v10
	s_add_i32 s22, s22, 1
	v_cmp_lt_i32_e32 vcc, 5, v4
	s_cbranch_vccnz .Lrs1_issued
	v_lshl_add_u64 v[2:3], v[2:3], 0, s[12:13]
	v_cmp_gt_i64_e32 vcc, s[18:19], v[2:3]
	s_cbranch_vccz .Lrs1_issued
	v_ashrrev_i32_e32 v78, 31, v10
	v_lshrrev_b32_e32 v78, 29, v78
	v_add_u32_e32 v78, v10, v78
	v_ashrrev_i32_e32 v80, 3, v78
	v_and_b32_e32 v78, -8, v78
	v_sub_u32_e32 v78, v10, v78
	v_cmp_gt_i32_e32 vcc, 0, v78
	v_add_u32_e32 v4, 2, v4
	s_nop 0
	v_cndmask_b32_e32 v81, v7, v8, vcc
	v_mad_u64_u32 v[80:81], s[4:5], v81, v78, v[80:81]
	v_mul_hi_i32 v78, v80, s17
	v_lshrrev_b32_e32 v81, 31, v78
	v_ashrrev_i32_e32 v78, 4, v78
	v_add_u32_e32 v78, v78, v81
	v_mul_lo_u32 v81, v78, s25
	v_sub_u32_e32 v80, v80, v81
	v_lshrrev_b16_sdwa v81, v9, sext(v80) dst_sel:DWORD dst_unused:UNUSED_PAD src0_sel:DWORD src1_sel:BYTE_0
	v_and_b32_e32 v81, 3, v81
	v_add_u16_e32 v81, v80, v81
	v_and_b32_e32 v81, 0xfc, v81
	v_sub_u16_e32 v80, v80, v81
	v_bfe_i32 v80, v80, 0, 8
	v_lshlrev_b32_e32 v78, 10, v78
	v_lshl_add_u32 v78, v80, 8, v78
	v_or_b32_sdwa v80, v78, v1 dst_sel:DWORD dst_unused:UNUSED_PAD src0_sel:DWORD src1_sel:BYTE_0
	v_ashrrev_i32_e32 v81, 31, v80
	v_lshlrev_b64 v[80:81], 6, v[80:81]
	v_lshl_add_u64 v[82:83], s[10:11], 0, v[80:81]
	global_load_dwordx4 v[30:33], v[82:83], off
	global_load_dwordx4 v[34:37], v[82:83], off offset:32
	global_load_dwordx4 v[38:41], v[82:83], off offset:16
	global_load_dwordx4 v[42:45], v[82:83], off offset:48
	v_add_u32_e32 v10, s24, v10
	s_add_i32 s22, s22, 1
	v_cmp_lt_i32_e32 vcc, 5, v4
	s_cbranch_vccnz .Lrs1_issued
	v_lshl_add_u64 v[2:3], v[2:3], 0, s[12:13]
	v_cmp_gt_i64_e32 vcc, s[18:19], v[2:3]
	s_cbranch_vccz .Lrs1_issued
	v_ashrrev_i32_e32 v78, 31, v10
	v_lshrrev_b32_e32 v78, 29, v78
	v_add_u32_e32 v78, v10, v78
	v_ashrrev_i32_e32 v80, 3, v78
	v_and_b32_e32 v78, -8, v78
	v_sub_u32_e32 v78, v10, v78
	v_cmp_gt_i32_e32 vcc, 0, v78
	v_add_u32_e32 v4, 2, v4
	s_nop 0
	v_cndmask_b32_e32 v81, v7, v8, vcc
	v_mad_u64_u32 v[80:81], s[4:5], v81, v78, v[80:81]
	v_mul_hi_i32 v78, v80, s17
	v_lshrrev_b32_e32 v81, 31, v78
	v_ashrrev_i32_e32 v78, 4, v78
	v_add_u32_e32 v78, v78, v81
	v_mul_lo_u32 v81, v78, s25
	v_sub_u32_e32 v80, v80, v81
	v_lshrrev_b16_sdwa v81, v9, sext(v80) dst_sel:DWORD dst_unused:UNUSED_PAD src0_sel:DWORD src1_sel:BYTE_0
	v_and_b32_e32 v81, 3, v81
	v_add_u16_e32 v81, v80, v81
	v_and_b32_e32 v81, 0xfc, v81
	v_sub_u16_e32 v80, v80, v81
	v_bfe_i32 v80, v80, 0, 8
	v_lshlrev_b32_e32 v78, 10, v78
	v_lshl_add_u32 v78, v80, 8, v78
	v_or_b32_sdwa v80, v78, v1 dst_sel:DWORD dst_unused:UNUSED_PAD src0_sel:DWORD src1_sel:BYTE_0
	v_ashrrev_i32_e32 v81, 31, v80
	v_lshlrev_b64 v[80:81], 6, v[80:81]
	v_lshl_add_u64 v[82:83], s[10:11], 0, v[80:81]
	global_load_dwordx4 v[46:49], v[82:83], off
	global_load_dwordx4 v[50:53], v[82:83], off offset:32
	global_load_dwordx4 v[54:57], v[82:83], off offset:16
	global_load_dwordx4 v[58:61], v[82:83], off offset:48
	v_add_u32_e32 v10, s24, v10
	s_add_i32 s22, s22, 1
	v_cmp_lt_i32_e32 vcc, 5, v4
	s_cbranch_vccnz .Lrs1_issued
	v_lshl_add_u64 v[2:3], v[2:3], 0, s[12:13]
	v_cmp_gt_i64_e32 vcc, s[18:19], v[2:3]
	s_cbranch_vccz .Lrs1_issued
	v_ashrrev_i32_e32 v78, 31, v10
	v_lshrrev_b32_e32 v78, 29, v78
	v_add_u32_e32 v78, v10, v78
	v_ashrrev_i32_e32 v80, 3, v78
	v_and_b32_e32 v78, -8, v78
	v_sub_u32_e32 v78, v10, v78
	v_cmp_gt_i32_e32 vcc, 0, v78
	v_add_u32_e32 v4, 2, v4
	s_nop 0
	v_cndmask_b32_e32 v81, v7, v8, vcc
	v_mad_u64_u32 v[80:81], s[4:5], v81, v78, v[80:81]
	v_mul_hi_i32 v78, v80, s17
	v_lshrrev_b32_e32 v81, 31, v78
	v_ashrrev_i32_e32 v78, 4, v78
	v_add_u32_e32 v78, v78, v81
	v_mul_lo_u32 v81, v78, s25
	v_sub_u32_e32 v80, v80, v81
	v_lshrrev_b16_sdwa v81, v9, sext(v80) dst_sel:DWORD dst_unused:UNUSED_PAD src0_sel:DWORD src1_sel:BYTE_0
	v_and_b32_e32 v81, 3, v81
	v_add_u16_e32 v81, v80, v81
	v_and_b32_e32 v81, 0xfc, v81
	v_sub_u16_e32 v80, v80, v81
	v_bfe_i32 v80, v80, 0, 8
	v_lshlrev_b32_e32 v78, 10, v78
	v_lshl_add_u32 v78, v80, 8, v78
	v_or_b32_sdwa v80, v78, v1 dst_sel:DWORD dst_unused:UNUSED_PAD src0_sel:DWORD src1_sel:BYTE_0
	v_ashrrev_i32_e32 v81, 31, v80
	v_lshlrev_b64 v[80:81], 6, v[80:81]
	v_lshl_add_u64 v[82:83], s[10:11], 0, v[80:81]
	global_load_dwordx4 v[62:65], v[82:83], off
	global_load_dwordx4 v[66:69], v[82:83], off offset:32
	global_load_dwordx4 v[70:73], v[82:83], off offset:16
	global_load_dwordx4 v[74:77], v[82:83], off offset:48
	v_add_u32_e32 v10, s24, v10
	s_add_i32 s22, s22, 1

.Lrs1_r_0:
	v_mov_b32_e32 v10, v12
	v_mov_b32_e32 v11, v16
	v_mov_b32_e32 v16, v13
	v_mov_b32_e32 v12, v14
	v_mov_b32_e32 v13, v18
	v_mov_b32_e32 v18, v15
	v_mov_b32_e32 v14, v20
	v_mov_b32_e32 v15, v24
	v_mov_b32_e32 v24, v21
	v_mov_b32_e32 v20, v22
	v_mov_b32_e32 v21, v26
	v_mov_b32_e32 v26, v23
	v_pk_add_f32 v[10:11], v[10:11], v[16:17]
	v_pk_add_f32 v[12:13], v[12:13], v[18:19]
	v_pk_add_f32 v[14:15], v[14:15], v[24:25]
	v_pk_add_f32 v[16:17], v[20:21], v[26:27]
	v_pk_add_f32 v[10:11], v[10:11], v[12:13]
	v_pk_add_f32 v[12:13], v[14:15], v[16:17]
	s_nop 0
	v_pk_add_f32 v[10:11], v[10:11], v[12:13]
	s_nop 0
	v_add_f32_e32 v10, v10, v11
	v_fmamk_f32 v10, v10, 0x3a800000, v6
	v_mul_f32_e32 v11, 0x4b800000, v10
	v_cmp_gt_f32_e32 vcc, s26, v10
	s_nop 1
	v_cndmask_b32_e32 v10, v10, v11, vcc
	v_rsq_f32_e32 v10, v10
	s_nop 0
	v_mul_f32_e32 v11, 0x45800000, v10
	v_cndmask_b32_e32 v10, v10, v11, vcc
	ds_write_b32 v5, v10
	v_add_u32_e32 v5, 0x800, v5
	s_cmp_le_u32 s22, 1
	s_cbranch_scc1 .Lrs1_done
	s_cmp_eq_u32 s22, 2
	s_cbranch_scc1 .Lrs1_w0_1
	s_waitcnt vmcnt(4)
	s_branch .Lrs1_r_1

.Lrs1_r_1:
	v_mov_b32_e32 v10, v30
	v_mov_b32_e32 v11, v34
	v_mov_b32_e32 v34, v31
	v_mov_b32_e32 v30, v32
	v_mov_b32_e32 v31, v36
	v_mov_b32_e32 v36, v33
	v_mov_b32_e32 v32, v38
	v_mov_b32_e32 v33, v42
	v_mov_b32_e32 v42, v39
	v_mov_b32_e32 v38, v40
	v_mov_b32_e32 v39, v44
	v_mov_b32_e32 v44, v41
	v_pk_add_f32 v[10:11], v[10:11], v[34:35]
	v_pk_add_f32 v[30:31], v[30:31], v[36:37]
	v_pk_add_f32 v[32:33], v[32:33], v[42:43]
	v_pk_add_f32 v[34:35], v[38:39], v[44:45]
	v_pk_add_f32 v[10:11], v[10:11], v[30:31]
	v_pk_add_f32 v[30:31], v[32:33], v[34:35]
	s_nop 0
	v_pk_add_f32 v[10:11], v[10:11], v[30:31]
	s_nop 0
	v_add_f32_e32 v10, v10, v11
	v_fmamk_f32 v10, v10, 0x3a800000, v6
	v_mul_f32_e32 v11, 0x4b800000, v10
	v_cmp_gt_f32_e32 vcc, s26, v10
	s_nop 1
	v_cndmask_b32_e32 v10, v10, v11, vcc
	v_rsq_f32_e32 v10, v10
	s_nop 0
	v_mul_f32_e32 v11, 0x45800000, v10
	v_cndmask_b32_e32 v10, v10, v11, vcc
	ds_write_b32 v5, v10
	v_add_u32_e32 v5, 0x800, v5
	s_cmp_le_u32 s22, 2
	s_cbranch_scc1 .Lrs1_done
	s_cmp_eq_u32 s22, 3
	s_cbranch_scc1 .Lrs1_w0_2
	s_waitcnt vmcnt(4)
	s_branch .Lrs1_r_2

.Lrs1_r_2:
	v_mov_b32_e32 v10, v46
	v_mov_b32_e32 v11, v50
	v_mov_b32_e32 v50, v47
	v_mov_b32_e32 v46, v48
	v_mov_b32_e32 v47, v52
	v_mov_b32_e32 v52, v49
	v_mov_b32_e32 v48, v54
	v_mov_b32_e32 v49, v58
	v_mov_b32_e32 v58, v55
	v_mov_b32_e32 v54, v56
	v_mov_b32_e32 v55, v60
	v_mov_b32_e32 v60, v57
	v_pk_add_f32 v[10:11], v[10:11], v[50:51]
	v_pk_add_f32 v[46:47], v[46:47], v[52:53]
	v_pk_add_f32 v[48:49], v[48:49], v[58:59]
	v_pk_add_f32 v[50:51], v[54:55], v[60:61]
	v_pk_add_f32 v[10:11], v[10:11], v[46:47]
	v_pk_add_f32 v[46:47], v[48:49], v[50:51]
	s_nop 0
	v_pk_add_f32 v[10:11], v[10:11], v[46:47]
	s_nop 0
	v_add_f32_e32 v10, v10, v11
	v_fmamk_f32 v10, v10, 0x3a800000, v6
	v_mul_f32_e32 v11, 0x4b800000, v10
	v_cmp_gt_f32_e32 vcc, s26, v10
	s_nop 1
	v_cndmask_b32_e32 v10, v10, v11, vcc
	v_rsq_f32_e32 v10, v10
	s_nop 0
	v_mul_f32_e32 v11, 0x45800000, v10
	v_cndmask_b32_e32 v10, v10, v11, vcc
	ds_write_b32 v5, v10
	v_add_u32_e32 v5, 0x800, v5
	s_cmp_le_u32 s22, 3
	s_cbranch_scc1 .Lrs1_done
	s_cmp_eq_u32 s22, 4
	s_cbranch_scc1 .Lrs1_w0_3
	s_waitcnt vmcnt(4)
	s_branch .Lrs1_r_3

.Lrs1_r_3:
	v_mov_b32_e32 v10, v62
	v_mov_b32_e32 v11, v66
	v_mov_b32_e32 v66, v63
	v_mov_b32_e32 v62, v64
	v_mov_b32_e32 v63, v68
	v_mov_b32_e32 v68, v65
	v_mov_b32_e32 v64, v70
	v_mov_b32_e32 v65, v74
	v_mov_b32_e32 v74, v71
	v_mov_b32_e32 v70, v72
	v_mov_b32_e32 v71, v76
	v_mov_b32_e32 v76, v73
	v_pk_add_f32 v[10:11], v[10:11], v[66:67]
	v_pk_add_f32 v[62:63], v[62:63], v[68:69]
	v_pk_add_f32 v[64:65], v[64:65], v[74:75]
	v_pk_add_f32 v[66:67], v[70:71], v[76:77]
	v_pk_add_f32 v[10:11], v[10:11], v[62:63]
	v_pk_add_f32 v[62:63], v[64:65], v[66:67]
	s_nop 0
	v_pk_add_f32 v[10:11], v[10:11], v[62:63]
	s_nop 0
	v_add_f32_e32 v10, v10, v11
	v_fmamk_f32 v10, v10, 0x3a800000, v6
	v_mul_f32_e32 v11, 0x4b800000, v10
	v_cmp_gt_f32_e32 vcc, s26, v10
	s_nop 1
	v_cndmask_b32_e32 v10, v10, v11, vcc
	v_rsq_f32_e32 v10, v10
	s_nop 0
	v_mul_f32_e32 v11, 0x45800000, v10
	v_cndmask_b32_e32 v10, v10, v11, vcc
	ds_write_b32 v5, v10
	v_add_u32_e32 v5, 0x800, v5
.Lrs1_done:
	s_branch .LBB0_511
.LBB0_511:
	s_or_b64 exec, exec, s[8:9]
	s_waitcnt lgkmcnt(0)
	s_barrier
	v_mov_b32_e32 v2, v0
	s_cmpk_gt_i32 s3, 0x57f
	v_readfirstlane_b32 s6, v2
	s_cbranch_scc1 .LBB0_527
	v_bfe_i32 v4, v2, 27, 1
	v_lshlrev_b32_e32 v3, 4, v2
	v_lshrrev_b32_e32 v4, 22, v4
	v_add_u32_e32 v4, v3, v4
	v_and_b32_e32 v4, 0xfffffc00, v4
	v_sub_u32_e32 v4, v3, v4
	v_ashrrev_i32_e32 v1, 31, v2
	v_lshrrev_b32_e32 v5, 4, v4
	v_lshrrev_b32_e32 v1, 26, v1
	v_bitop3_b32 v4, v5, v4, 32 bitop3:0x6c
	v_add_u32_e32 v1, v2, v1
	v_ashrrev_i32_e32 v6, 31, v4
	v_ashrrev_i32_e32 v1, 6, v1
	v_lshrrev_b32_e32 v6, 26, v6
	v_lshlrev_b32_e32 v5, 3, v1
	v_add_u32_e32 v6, v4, v6
	v_and_b32_e32 v5, -16, v5
	v_ashrrev_i32_e32 v7, 6, v6
	v_and_b32_e32 v6, 0xc0, v6
	v_add_u32_e32 v5, v7, v5
	v_sub_u32_e32 v4, v4, v6
	v_mov_b32_e32 v6, 1
	v_lshlrev_b32_e32 v1, 5, v1
	v_ashrrev_i16_sdwa v4, v6, sext(v4) dst_sel:DWORD dst_unused:UNUSED_PAD src0_sel:DWORD src1_sel:BYTE_0
	v_lshlrev_b32_e32 v8, 1, v5
	v_lshrrev_b32_e32 v9, 2, v5
	v_and_b32_e32 v7, 3, v7
	s_mov_b32 s4, 0x1fffe0
	v_and_b32_e32 v1, 32, v1
	v_bfe_i32 v4, v4, 0, 16
	v_and_b32_e32 v8, 24, v8
	v_and_b32_e32 v9, 4, v9
	v_and_or_b32 v7, v5, s4, v7
	v_or3_b32 v7, v7, v9, v8
	v_add_lshl_u32 v4, v1, v4, 1
	v_add_u32_e32 v3, 0x2000, v3
	v_lshl_add_u32 v1, v5, 11, v4
	v_lshl_add_u32 v140, v7, 11, v4
	v_ashrrev_i32_e32 v4, 31, v3
	v_lshrrev_b32_e32 v4, 22, v4
	v_add_u32_e32 v4, v3, v4
	v_ashrrev_i32_e32 v4, 10, v4
	v_mul_i32_i24_e32 v5, 0x400, v4
	v_sub_u32_e32 v3, v3, v5
	v_lshrrev_b32_e32 v5, 4, v3
	v_bitop3_b32 v3, v5, v3, 32 bitop3:0x6c
	v_ashrrev_i32_e32 v7, 31, v3
	v_lshrrev_b32_e32 v7, 26, v7
	v_lshlrev_b32_e32 v5, 3, v4
	v_add_u32_e32 v7, v3, v7
	v_and_b32_e32 v5, -16, v5
	v_ashrrev_i32_e32 v8, 6, v7
	v_add_u32_e32 v5, v8, v5
	v_and_b32_e32 v8, 3, v8
	s_ashr_i32 s22, s6, 6
	s_ashr_i32 s7, s6, 8
	v_and_or_b32 v8, v5, s4, v8
	s_lshl_b32 s4, s22, 10
	s_waitcnt lgkmcnt(0)
	s_add_u32 s8, s20, 0x3a00000
	s_addc_u32 s5, s21, 0
	s_add_u32 s12, s20, 0xa00000
	s_addc_u32 s9, s21, 0
	s_ashr_i32 s17, s3, 31
	s_lshr_b32 s10, s17, 29
	s_add_i32 s10, s3, s10
	s_ashr_i32 s11, s10, 3
	s_and_b32 s10, s10, -8
	s_sub_i32 s10, s3, s10
	s_cmp_lt_i32 s10, 0
	s_movk_i32 s24, 0xb1
	s_cselect_b32 s13, s24, 0xb0
	s_mul_i32 s10, s13, s10
	s_add_i32 s10, s10, s11
	s_mul_hi_i32 s11, s10, 0x2e8ba2e9
	s_lshr_b32 s13, s11, 31
	s_ashr_i32 s11, s11, 4
	s_add_i32 s11, s11, s13
	s_lshl_b32 s13, s11, 2
	s_mulk_i32 s11, 0x58
	s_sub_i32 s10, s10, s11
	s_bfe_i32 s11, s10, 0x80000
	s_bfe_u32 s11, s11, 0x2000d
	v_and_b32_e32 v7, 0xc0, v7
	s_add_i32 s11, s10, s11
	v_sub_u32_e32 v3, v3, v7
	s_bfe_i32 s14, s11, 0x80000
	s_and_b32 s11, s11, 0xfc
	v_lshlrev_b32_e32 v4, 5, v4
	v_ashrrev_i16_sdwa v3, v6, sext(v3) dst_sel:DWORD dst_unused:UNUSED_PAD src0_sel:DWORD src1_sel:BYTE_0
	v_lshlrev_b32_e32 v6, 1, v5
	v_lshrrev_b32_e32 v7, 2, v5
	s_sext_i32_i16 s14, s14
	s_sub_i32 s10, s10, s11
	s_add_i32 s25, s4, 0
	v_and_b32_e32 v4, 32, v4
	v_bfe_i32 v3, v3, 0, 16
	v_and_b32_e32 v6, 24, v6
	v_and_b32_e32 v7, 4, v7
	s_sext_i32_i8 s10, s10
	s_ashr_i32 s54, s14, 2
	s_add_i32 s26, s25, 0x10000
	v_or3_b32 v6, v8, v7, v6
	v_add_lshl_u32 v3, v4, v3, 1
	s_add_i32 s53, s13, s10
	s_and_b32 s13, s9, 0xffff
	s_mov_b32 s15, 0x20000
	s_mov_b32 s14, 0x7ffffff0
	s_lshl_b32 s58, s54, 19
	s_mov_b32 m0, s26
	s_add_i32 s27, s25, 0x12000
	v_lshl_add_u32 v142, v6, 11, v3
	buffer_load_dwordx4 v140, s[12:15], s58 offen lds
	s_mov_b32 m0, s27
	s_add_i32 s28, s25, 0x14000
	buffer_load_dwordx4 v142, s[12:15], s58 offen lds
	s_or_b32 s4, s58, 0x40000
	s_mov_b32 m0, s28
	s_add_i32 s29, s25, 0x16000
	s_and_b32 s9, s5, 0xffff
	buffer_load_dwordx4 v140, s[12:15], s4 offen lds
	s_mov_b32 m0, s29
	s_mov_b32 s36, s8
	s_mov_b32 s37, s9
	s_mov_b32 s38, s14
	s_mov_b32 s39, s15
	buffer_load_dwordx4 v142, s[12:15], s4 offen lds
	s_lshl_b32 s59, s53, 19
	s_mov_b32 m0, s25
	s_add_i32 s30, s25, 0x2000
	v_lshl_add_u32 v141, v5, 11, v3
	buffer_load_dwordx4 v1, s[36:39], s59 offen lds
	s_mov_b32 m0, s30
	s_add_i32 s31, s25, 0x4000
	buffer_load_dwordx4 v141, s[36:39], s59 offen lds
	s_or_b32 s4, s59, 0x40000
	s_mov_b32 m0, s31
	s_add_i32 s34, s25, 0x6000
	buffer_load_dwordx4 v1, s[36:39], s4 offen lds
	s_mov_b32 m0, s34
	s_cmp_eq_u32 s7, 1
	buffer_load_dwordx4 v141, s[36:39], s4 offen lds
	s_mov_b32 s55, 0
	s_mov_b32 s10, s14
	s_cselect_b64 s[18:19], -1, 0
	s_cmp_lg_u32 s7, 1
	s_mov_b32 s11, s15
	s_cbranch_scc1 .LBB0_514
	s_barrier

.Lrs3_done:
	s_branch .LBB0_1625
.LBB0_1625:
	s_or_b64 exec, exec, s[8:9]
	s_waitcnt lgkmcnt(0)
	s_barrier
	v_mov_b32_e32 v2, v0
	s_cmpk_gt_i32 s3, 0x57f
	v_readfirstlane_b32 s6, v2
	s_cbranch_scc1 .LBB0_1641
	v_bfe_i32 v4, v2, 27, 1
	v_lshlrev_b32_e32 v3, 4, v2
	v_lshrrev_b32_e32 v4, 22, v4
	v_add_u32_e32 v4, v3, v4
	v_and_b32_e32 v4, 0xfffffc00, v4
	v_sub_u32_e32 v4, v3, v4
	v_ashrrev_i32_e32 v1, 31, v2
	v_lshrrev_b32_e32 v5, 4, v4
	v_lshrrev_b32_e32 v1, 26, v1
	v_bitop3_b32 v4, v5, v4, 32 bitop3:0x6c
	v_add_u32_e32 v1, v2, v1
	v_ashrrev_i32_e32 v6, 31, v4
	v_ashrrev_i32_e32 v1, 6, v1
	v_lshrrev_b32_e32 v6, 26, v6
	v_lshlrev_b32_e32 v5, 3, v1
	v_add_u32_e32 v6, v4, v6
	v_and_b32_e32 v5, -16, v5
	v_ashrrev_i32_e32 v7, 6, v6
	v_and_b32_e32 v6, 0xc0, v6
	v_add_u32_e32 v5, v7, v5
	v_sub_u32_e32 v4, v4, v6
	v_mov_b32_e32 v6, 1
	v_lshlrev_b32_e32 v1, 5, v1
	v_ashrrev_i16_sdwa v4, v6, sext(v4) dst_sel:DWORD dst_unused:UNUSED_PAD src0_sel:DWORD src1_sel:BYTE_0
	v_lshlrev_b32_e32 v8, 1, v5
	v_lshrrev_b32_e32 v9, 2, v5
	v_and_b32_e32 v7, 3, v7
	s_mov_b32 s4, 0x1fffe0
	v_and_b32_e32 v1, 32, v1
	v_bfe_i32 v4, v4, 0, 16
	v_and_b32_e32 v8, 24, v8
	v_and_b32_e32 v9, 4, v9
	v_and_or_b32 v7, v5, s4, v7
	v_or3_b32 v7, v7, v9, v8
	v_add_lshl_u32 v4, v1, v4, 1
	v_add_u32_e32 v3, 0x2000, v3
	v_lshl_add_u32 v1, v5, 11, v4
	v_lshl_add_u32 v140, v7, 11, v4
	v_ashrrev_i32_e32 v4, 31, v3
	v_lshrrev_b32_e32 v4, 22, v4
	v_add_u32_e32 v4, v3, v4
	v_ashrrev_i32_e32 v4, 10, v4
	v_mul_i32_i24_e32 v5, 0x400, v4
	v_sub_u32_e32 v3, v3, v5
	v_lshrrev_b32_e32 v5, 4, v3
	v_bitop3_b32 v3, v5, v3, 32 bitop3:0x6c
	v_ashrrev_i32_e32 v7, 31, v3
	v_lshrrev_b32_e32 v7, 26, v7
	v_lshlrev_b32_e32 v5, 3, v4
	v_add_u32_e32 v7, v3, v7
	v_and_b32_e32 v5, -16, v5
	v_ashrrev_i32_e32 v8, 6, v7
	v_add_u32_e32 v5, v8, v5
	v_and_b32_e32 v8, 3, v8
	s_ashr_i32 s22, s6, 6
	s_ashr_i32 s7, s6, 8
	v_and_or_b32 v8, v5, s4, v8
	s_lshl_b32 s4, s22, 10
	s_waitcnt lgkmcnt(0)
	s_add_u32 s8, s20, 0x3a00000
	s_addc_u32 s5, s21, 0
	s_add_u32 s12, s20, 0x2480000
	s_addc_u32 s9, s21, 0
	s_ashr_i32 s17, s3, 31
	s_lshr_b32 s10, s17, 29
	s_add_i32 s10, s3, s10
	s_ashr_i32 s11, s10, 3
	s_and_b32 s10, s10, -8
	s_sub_i32 s10, s3, s10
	s_cmp_lt_i32 s10, 0
	s_movk_i32 s24, 0xb1
	s_cselect_b32 s13, s24, 0xb0
	s_mul_i32 s10, s13, s10
	s_add_i32 s10, s10, s11
	s_mul_hi_i32 s11, s10, 0x2e8ba2e9
	s_lshr_b32 s13, s11, 31
	s_ashr_i32 s11, s11, 4
	s_add_i32 s11, s11, s13
	s_lshl_b32 s13, s11, 2
	s_mulk_i32 s11, 0x58
	s_sub_i32 s10, s10, s11
	s_bfe_i32 s11, s10, 0x80000
	s_bfe_u32 s11, s11, 0x2000d
	v_and_b32_e32 v7, 0xc0, v7
	s_add_i32 s11, s10, s11
	v_sub_u32_e32 v3, v3, v7
	s_bfe_i32 s14, s11, 0x80000
	s_and_b32 s11, s11, 0xfc
	v_lshlrev_b32_e32 v4, 5, v4
	v_ashrrev_i16_sdwa v3, v6, sext(v3) dst_sel:DWORD dst_unused:UNUSED_PAD src0_sel:DWORD src1_sel:BYTE_0
	v_lshlrev_b32_e32 v6, 1, v5
	v_lshrrev_b32_e32 v7, 2, v5
	s_sext_i32_i16 s14, s14
	s_sub_i32 s10, s10, s11
	s_add_i32 s25, s4, 0
	v_and_b32_e32 v4, 32, v4
	v_bfe_i32 v3, v3, 0, 16
	v_and_b32_e32 v6, 24, v6
	v_and_b32_e32 v7, 4, v7
	s_sext_i32_i8 s10, s10
	s_ashr_i32 s54, s14, 2
	s_add_i32 s26, s25, 0x10000
	v_or3_b32 v6, v8, v7, v6
	v_add_lshl_u32 v3, v4, v3, 1
	s_add_i32 s53, s13, s10
	s_and_b32 s13, s9, 0xffff
	s_mov_b32 s15, 0x20000
	s_mov_b32 s14, 0x7ffffff0
	s_lshl_b32 s58, s54, 19
	s_mov_b32 m0, s26
	s_add_i32 s27, s25, 0x12000
	v_lshl_add_u32 v142, v6, 11, v3
	buffer_load_dwordx4 v140, s[12:15], s58 offen lds
	s_mov_b32 m0, s27
	s_add_i32 s28, s25, 0x14000
	buffer_load_dwordx4 v142, s[12:15], s58 offen lds
	s_or_b32 s4, s58, 0x40000
	s_mov_b32 m0, s28
	s_add_i32 s29, s25, 0x16000
	s_and_b32 s9, s5, 0xffff
	buffer_load_dwordx4 v140, s[12:15], s4 offen lds
	s_mov_b32 m0, s29
	s_mov_b32 s36, s8
	s_mov_b32 s37, s9
	s_mov_b32 s38, s14
	s_mov_b32 s39, s15
	buffer_load_dwordx4 v142, s[12:15], s4 offen lds
	s_lshl_b32 s59, s53, 19
	s_mov_b32 m0, s25
	s_add_i32 s30, s25, 0x2000
	v_lshl_add_u32 v141, v5, 11, v3
	buffer_load_dwordx4 v1, s[36:39], s59 offen lds
	s_mov_b32 m0, s30
	s_add_i32 s31, s25, 0x4000
	buffer_load_dwordx4 v141, s[36:39], s59 offen lds
	s_or_b32 s4, s59, 0x40000
	s_mov_b32 m0, s31
	s_add_i32 s34, s25, 0x6000
	buffer_load_dwordx4 v1, s[36:39], s4 offen lds
	s_mov_b32 m0, s34
	s_cmp_eq_u32 s7, 1
	buffer_load_dwordx4 v141, s[36:39], s4 offen lds
	s_mov_b32 s55, 0
	s_mov_b32 s10, s14
	s_cselect_b64 s[18:19], -1, 0
	s_cmp_lg_u32 s7, 1
	s_mov_b32 s11, s15
	s_cbranch_scc1 .LBB0_1628
	s_barrier
